# 8-deep decode batches beside the recurrence (two waves)
# speedup vs baseline: 1.0423x; 1.0423x over previous
; __device__ __forceinline__ void sb_decode_wave_loop(const Params& P, float* lds) {
;     ...
;         bool thin = false;
;         bool scan_running = false;
;         if (SC_THIN && blockIdx.x < 96) { constexpr unsigned NCHU = SEQ / 16; scan_running = scw[1] < NCHU || scw[2] < NCHU || scw[3] < NCHU || scw[4] < NCHU; thin = scan_running; }
;         thin = true;
;         if (blockIdx.x < 96 && scan_running) { sb_decode_task<4>(P, lds, t); sb_decode_task<4>(P, lds, t + 1); }
;         else if (thin) { sb_decode_task<8>(P, lds, t); sb_decode_task<8>(P, lds, t + 1); }
.LBB0_1274:
	s_or_b64 exec, exec, s[0:1]
	s_and_b64 vcc, exec, s[22:23]
	s_branch .LBB0_1279
	v_mov_b32_e32 v2, s42
	ds_read_b32 v2, v2
	s_movk_i32 s3, 0xff
	s_movk_i32 s2, 0x100
	s_waitcnt lgkmcnt(0)
	v_cmp_lt_u32_e32 vcc, s3, v2
	v_cmp_gt_u32_e64 s[0:1], s2, v2
	s_cbranch_vccz .LBB0_1280
	v_readlane_b32 s0, v252, 60
	s_nop 1
	v_mov_b32_e32 v2, s0
	ds_read_b32 v2, v2
	s_waitcnt lgkmcnt(0)
	v_cmp_lt_u32_e32 vcc, s3, v2
	v_cmp_gt_u32_e64 s[0:1], s2, v2
	s_cbranch_vccz .LBB0_1280
	v_readlane_b32 s0, v252, 58
	s_nop 1
	v_mov_b32_e32 v2, s0
	ds_read_b32 v2, v2
	s_waitcnt lgkmcnt(0)
	v_cmp_lt_u32_e32 vcc, s3, v2
	v_cmp_gt_u32_e64 s[0:1], s2, v2
	s_cbranch_vccz .LBB0_1280
	v_mov_b32_e32 v2, s94
	ds_read_b32 v2, v2
	s_mov_b64 s[0:1], -1
	s_waitcnt lgkmcnt(0)
	v_cmp_lt_u32_e64 s[2:3], s3, v2
	s_and_b64 vcc, exec, s[2:3]
	s_mul_hi_i32 s2, s34, 0x2aaaaaab
	s_cbranch_vccnz .LBB0_1281
	s_branch .LBB0_1418
